# SwiGLU epilogue: write-through (sc1) H stores only for context units; latent units use plain write-back stores
# speedup vs baseline: 1.0064x; 1.0037x over previous
.LBB0_85:
	s_cmp_lt_i32 s50, 64
	s_cbranch_scc0 .Lmy_swi_ctx
	v_lshl_or_b32 v144, s26, 7, v147
	v_readlane_b32 s26, v252, 5
	v_readlane_b32 s27, v252, 6
	v_lshl_add_u32 v149, s50, 8, v37
	v_ashrrev_i32_e32 v145, 31, v144
	s_movk_i32 s0, 0x1600
	s_mov_b32 vcc_lo, 0xbfb8aa3b
	s_mov_b32 vcc_hi, 0xbfb8aa3b
	v_lshlrev_b64 v[144:145], 1, v[144:145]
	v_mov_b64_e32 v[142:143], s[26:27]
	v_mad_i64_i32 v[150:151], s[26:27], v149, s0, v[142:143]
	v_pk_mul_f32 v[126:127], v[130:131], v[126:127]
	v_pk_mul_f32 v[128:129], v[132:133], v[128:129]
	v_pk_mul_f32 v[118:119], v[122:123], v[118:119]
	v_pk_mul_f32 v[120:121], v[124:125], v[120:121]
	v_pk_mul_f32 v[130:131], v[130:131], vcc op_sel_hi:[1,0]
	v_pk_mul_f32 v[132:133], v[132:133], vcc op_sel_hi:[1,0]
	v_pk_mul_f32 v[122:123], v[122:123], vcc op_sel_hi:[1,0]
	v_pk_mul_f32 v[124:125], v[124:125], vcc op_sel_hi:[1,0]
	v_exp_f32_e32 v130, v130
	v_exp_f32_e32 v131, v131
	v_exp_f32_e32 v132, v132
	v_exp_f32_e32 v133, v133
	v_exp_f32_e32 v122, v122
	v_exp_f32_e32 v123, v123
	v_exp_f32_e32 v124, v124
	v_exp_f32_e32 v125, v125
	v_pk_add_f32 v[130:131], v[130:131], 1.0 op_sel_hi:[1,0]
	v_pk_add_f32 v[132:133], v[132:133], 1.0 op_sel_hi:[1,0]
	v_pk_add_f32 v[122:123], v[122:123], 1.0 op_sel_hi:[1,0]
	v_pk_add_f32 v[124:125], v[124:125], 1.0 op_sel_hi:[1,0]
	v_rcp_f32_e32 v130, v130
	v_rcp_f32_e32 v131, v131
	v_rcp_f32_e32 v132, v132
	v_rcp_f32_e32 v133, v133
	v_rcp_f32_e32 v122, v122
	v_rcp_f32_e32 v123, v123
	v_rcp_f32_e32 v124, v124
	v_rcp_f32_e32 v125, v125
	v_pk_mul_f32 v[126:127], v[126:127], v[130:131]
	v_pk_mul_f32 v[128:129], v[128:129], v[132:133]
	v_pk_mul_f32 v[118:119], v[118:119], v[122:123]
	v_pk_mul_f32 v[120:121], v[120:121], v[124:125]
	v_cvt_pk_bf16_f32 v130, v126, v127
	v_cvt_pk_bf16_f32 v131, v128, v129
	v_cvt_pk_bf16_f32 v132, v118, v119
	v_cvt_pk_bf16_f32 v133, v120, v121
	v_lshl_add_u64 v[150:151], v[150:151], 0, v[144:145]
	global_store_dwordx4 v[150:151], v[130:133], off
	v_pk_mul_f32 v[110:111], v[114:115], v[110:111]
	v_pk_mul_f32 v[112:113], v[116:117], v[112:113]
	v_pk_mul_f32 v[102:103], v[106:107], v[102:103]
	v_pk_mul_f32 v[104:105], v[108:109], v[104:105]
	v_pk_mul_f32 v[114:115], v[114:115], vcc op_sel_hi:[1,0]
	v_pk_mul_f32 v[116:117], v[116:117], vcc op_sel_hi:[1,0]
	v_pk_mul_f32 v[106:107], v[106:107], vcc op_sel_hi:[1,0]
	v_pk_mul_f32 v[108:109], v[108:109], vcc op_sel_hi:[1,0]
	v_exp_f32_e32 v114, v114
	v_exp_f32_e32 v115, v115
	v_exp_f32_e32 v116, v116
	v_exp_f32_e32 v117, v117
	v_exp_f32_e32 v106, v106
	v_exp_f32_e32 v107, v107
	v_exp_f32_e32 v108, v108
	v_exp_f32_e32 v109, v109
	v_pk_add_f32 v[114:115], v[114:115], 1.0 op_sel_hi:[1,0]
	v_pk_add_f32 v[116:117], v[116:117], 1.0 op_sel_hi:[1,0]
	v_pk_add_f32 v[106:107], v[106:107], 1.0 op_sel_hi:[1,0]
	v_pk_add_f32 v[108:109], v[108:109], 1.0 op_sel_hi:[1,0]
	v_rcp_f32_e32 v114, v114
	v_rcp_f32_e32 v115, v115
	v_rcp_f32_e32 v116, v116
	v_rcp_f32_e32 v117, v117
	v_rcp_f32_e32 v106, v106
	v_rcp_f32_e32 v107, v107
	v_rcp_f32_e32 v108, v108
	v_rcp_f32_e32 v109, v109
	v_pk_mul_f32 v[110:111], v[110:111], v[114:115]
	v_pk_mul_f32 v[112:113], v[112:113], v[116:117]
	v_pk_mul_f32 v[102:103], v[102:103], v[106:107]
	v_pk_mul_f32 v[104:105], v[104:105], v[108:109]
	v_cvt_pk_bf16_f32 v114, v110, v111
	v_cvt_pk_bf16_f32 v115, v112, v113
	v_cvt_pk_bf16_f32 v116, v102, v103
	v_cvt_pk_bf16_f32 v117, v104, v105
	s_mov_b32 s26, 0x16000
	s_mov_b32 s27, 0
	v_lshl_add_u64 v[118:119], v[150:151], 0, s[26:27]
	global_store_dwordx4 v[118:119], v[114:117], off
	v_pk_mul_f32 v[94:95], v[98:99], v[94:95]
	v_pk_mul_f32 v[96:97], v[100:101], v[96:97]
	v_pk_mul_f32 v[86:87], v[90:91], v[86:87]
	v_pk_mul_f32 v[88:89], v[92:93], v[88:89]
	v_pk_mul_f32 v[98:99], v[98:99], vcc op_sel_hi:[1,0]
	v_pk_mul_f32 v[100:101], v[100:101], vcc op_sel_hi:[1,0]
	v_pk_mul_f32 v[90:91], v[90:91], vcc op_sel_hi:[1,0]
	v_pk_mul_f32 v[92:93], v[92:93], vcc op_sel_hi:[1,0]
	v_exp_f32_e32 v98, v98
	v_exp_f32_e32 v99, v99
	v_exp_f32_e32 v100, v100
	v_exp_f32_e32 v101, v101
	v_exp_f32_e32 v90, v90
	v_exp_f32_e32 v91, v91
	v_exp_f32_e32 v92, v92
	v_exp_f32_e32 v93, v93
	v_pk_add_f32 v[98:99], v[98:99], 1.0 op_sel_hi:[1,0]
	v_pk_add_f32 v[100:101], v[100:101], 1.0 op_sel_hi:[1,0]
	v_pk_add_f32 v[90:91], v[90:91], 1.0 op_sel_hi:[1,0]
	v_pk_add_f32 v[92:93], v[92:93], 1.0 op_sel_hi:[1,0]
	v_rcp_f32_e32 v98, v98
	v_rcp_f32_e32 v99, v99
	v_rcp_f32_e32 v100, v100
	v_rcp_f32_e32 v101, v101
	v_rcp_f32_e32 v90, v90
	v_rcp_f32_e32 v91, v91
	v_rcp_f32_e32 v92, v92
	v_rcp_f32_e32 v93, v93
	v_pk_mul_f32 v[94:95], v[94:95], v[98:99]
	v_pk_mul_f32 v[96:97], v[96:97], v[100:101]
	v_pk_mul_f32 v[86:87], v[86:87], v[90:91]
	v_pk_mul_f32 v[88:89], v[88:89], v[92:93]
	v_cvt_pk_bf16_f32 v98, v94, v95
	v_cvt_pk_bf16_f32 v99, v96, v97
	v_cvt_pk_bf16_f32 v100, v86, v87
	v_cvt_pk_bf16_f32 v101, v88, v89
	s_mov_b32 s26, 0x2c000
	s_mov_b32 s27, 0
	v_lshl_add_u64 v[102:103], v[150:151], 0, s[26:27]
	global_store_dwordx4 v[102:103], v[98:101], off
	v_pk_mul_f32 v[78:79], v[82:83], v[78:79]
	v_pk_mul_f32 v[80:81], v[84:85], v[80:81]
	v_pk_mul_f32 v[70:71], v[74:75], v[70:71]
	v_pk_mul_f32 v[72:73], v[76:77], v[72:73]
	v_pk_mul_f32 v[82:83], v[82:83], vcc op_sel_hi:[1,0]
	v_pk_mul_f32 v[84:85], v[84:85], vcc op_sel_hi:[1,0]
	v_pk_mul_f32 v[74:75], v[74:75], vcc op_sel_hi:[1,0]
	v_pk_mul_f32 v[76:77], v[76:77], vcc op_sel_hi:[1,0]
	v_exp_f32_e32 v82, v82
	v_exp_f32_e32 v83, v83
	v_exp_f32_e32 v84, v84
	v_exp_f32_e32 v85, v85
	v_exp_f32_e32 v74, v74
	v_exp_f32_e32 v75, v75
	v_exp_f32_e32 v76, v76
	v_exp_f32_e32 v77, v77
	v_pk_add_f32 v[82:83], v[82:83], 1.0 op_sel_hi:[1,0]
	v_pk_add_f32 v[84:85], v[84:85], 1.0 op_sel_hi:[1,0]
	v_pk_add_f32 v[74:75], v[74:75], 1.0 op_sel_hi:[1,0]
	v_pk_add_f32 v[76:77], v[76:77], 1.0 op_sel_hi:[1,0]
	v_rcp_f32_e32 v82, v82
	v_rcp_f32_e32 v83, v83
	v_rcp_f32_e32 v84, v84
	v_rcp_f32_e32 v85, v85
	v_rcp_f32_e32 v74, v74
	v_rcp_f32_e32 v75, v75
	v_rcp_f32_e32 v76, v76
	v_rcp_f32_e32 v77, v77
	v_pk_mul_f32 v[78:79], v[78:79], v[82:83]
	v_pk_mul_f32 v[80:81], v[80:81], v[84:85]
	v_pk_mul_f32 v[70:71], v[70:71], v[74:75]
	v_pk_mul_f32 v[72:73], v[72:73], v[76:77]
	v_cvt_pk_bf16_f32 v82, v78, v79
	v_cvt_pk_bf16_f32 v83, v80, v81
	v_cvt_pk_bf16_f32 v84, v70, v71
	v_cvt_pk_bf16_f32 v85, v72, v73
	s_mov_b32 s26, 0x42000
	s_mov_b32 s27, 0
	v_lshl_add_u64 v[86:87], v[150:151], 0, s[26:27]
	global_store_dwordx4 v[86:87], v[82:85], off
	v_pk_mul_f32 v[62:63], v[66:67], v[62:63]
	v_pk_mul_f32 v[64:65], v[68:69], v[64:65]
	v_pk_mul_f32 v[54:55], v[58:59], v[54:55]
	v_pk_mul_f32 v[56:57], v[60:61], v[56:57]
	v_pk_mul_f32 v[66:67], v[66:67], vcc op_sel_hi:[1,0]
	v_pk_mul_f32 v[68:69], v[68:69], vcc op_sel_hi:[1,0]
	v_pk_mul_f32 v[58:59], v[58:59], vcc op_sel_hi:[1,0]
	v_pk_mul_f32 v[60:61], v[60:61], vcc op_sel_hi:[1,0]
	v_exp_f32_e32 v66, v66
	v_exp_f32_e32 v67, v67
	v_exp_f32_e32 v68, v68
	v_exp_f32_e32 v69, v69
	v_exp_f32_e32 v58, v58
	v_exp_f32_e32 v59, v59
	v_exp_f32_e32 v60, v60
	v_exp_f32_e32 v61, v61
	v_pk_add_f32 v[66:67], v[66:67], 1.0 op_sel_hi:[1,0]
	v_pk_add_f32 v[68:69], v[68:69], 1.0 op_sel_hi:[1,0]
	v_pk_add_f32 v[58:59], v[58:59], 1.0 op_sel_hi:[1,0]
	v_pk_add_f32 v[60:61], v[60:61], 1.0 op_sel_hi:[1,0]
	v_rcp_f32_e32 v66, v66
	v_rcp_f32_e32 v67, v67
	v_rcp_f32_e32 v68, v68
	v_rcp_f32_e32 v69, v69
	v_rcp_f32_e32 v58, v58
	v_rcp_f32_e32 v59, v59
	v_rcp_f32_e32 v60, v60
	v_rcp_f32_e32 v61, v61
	v_pk_mul_f32 v[62:63], v[62:63], v[66:67]
	v_pk_mul_f32 v[64:65], v[64:65], v[68:69]
	v_pk_mul_f32 v[54:55], v[54:55], v[58:59]
	v_pk_mul_f32 v[56:57], v[56:57], v[60:61]
	v_cvt_pk_bf16_f32 v66, v62, v63
	v_cvt_pk_bf16_f32 v67, v64, v65
	v_cvt_pk_bf16_f32 v68, v54, v55
	v_cvt_pk_bf16_f32 v69, v56, v57
	s_mov_b32 s26, 0xb0000
	s_mov_b32 s27, 0
	v_lshl_add_u64 v[70:71], v[150:151], 0, s[26:27]
	global_store_dwordx4 v[70:71], v[66:69], off
	v_pk_mul_f32 v[46:47], v[50:51], v[46:47]
	v_pk_mul_f32 v[48:49], v[52:53], v[48:49]
	v_pk_mul_f32 v[38:39], v[42:43], v[38:39]
	v_pk_mul_f32 v[40:41], v[44:45], v[40:41]
	v_pk_mul_f32 v[50:51], v[50:51], vcc op_sel_hi:[1,0]
	v_pk_mul_f32 v[52:53], v[52:53], vcc op_sel_hi:[1,0]
	v_pk_mul_f32 v[42:43], v[42:43], vcc op_sel_hi:[1,0]
	v_pk_mul_f32 v[44:45], v[44:45], vcc op_sel_hi:[1,0]
	v_exp_f32_e32 v50, v50
	v_exp_f32_e32 v51, v51
	v_exp_f32_e32 v52, v52
	v_exp_f32_e32 v53, v53
	v_exp_f32_e32 v42, v42
	v_exp_f32_e32 v43, v43
	v_exp_f32_e32 v44, v44
	v_exp_f32_e32 v45, v45
	v_pk_add_f32 v[50:51], v[50:51], 1.0 op_sel_hi:[1,0]
	v_pk_add_f32 v[52:53], v[52:53], 1.0 op_sel_hi:[1,0]
	v_pk_add_f32 v[42:43], v[42:43], 1.0 op_sel_hi:[1,0]
	v_pk_add_f32 v[44:45], v[44:45], 1.0 op_sel_hi:[1,0]
	v_rcp_f32_e32 v50, v50
	v_rcp_f32_e32 v51, v51
	v_rcp_f32_e32 v52, v52
	v_rcp_f32_e32 v53, v53
	v_rcp_f32_e32 v42, v42
	v_rcp_f32_e32 v43, v43
	v_rcp_f32_e32 v44, v44
	v_rcp_f32_e32 v45, v45
	v_pk_mul_f32 v[46:47], v[46:47], v[50:51]
	v_pk_mul_f32 v[48:49], v[48:49], v[52:53]
	v_pk_mul_f32 v[38:39], v[38:39], v[42:43]
	v_pk_mul_f32 v[40:41], v[40:41], v[44:45]
	v_cvt_pk_bf16_f32 v50, v46, v47
	v_cvt_pk_bf16_f32 v51, v48, v49
	v_cvt_pk_bf16_f32 v52, v38, v39
	v_cvt_pk_bf16_f32 v53, v40, v41
	s_mov_b32 s26, 0xc6000
	s_mov_b32 s27, 0
	v_lshl_add_u64 v[54:55], v[150:151], 0, s[26:27]
	global_store_dwordx4 v[54:55], v[50:53], off
	v_pk_mul_f32 v[24:25], v[28:29], v[24:25]
	v_pk_mul_f32 v[26:27], v[30:31], v[26:27]
	v_pk_mul_f32 v[16:17], v[20:21], v[16:17]
	v_pk_mul_f32 v[18:19], v[22:23], v[18:19]
	v_pk_mul_f32 v[28:29], v[28:29], vcc op_sel_hi:[1,0]
	v_pk_mul_f32 v[30:31], v[30:31], vcc op_sel_hi:[1,0]
	v_pk_mul_f32 v[20:21], v[20:21], vcc op_sel_hi:[1,0]
	v_pk_mul_f32 v[22:23], v[22:23], vcc op_sel_hi:[1,0]
	v_exp_f32_e32 v28, v28
	v_exp_f32_e32 v29, v29
	v_exp_f32_e32 v30, v30
	v_exp_f32_e32 v31, v31
	v_exp_f32_e32 v20, v20
	v_exp_f32_e32 v21, v21
	v_exp_f32_e32 v22, v22
	v_exp_f32_e32 v23, v23
	v_pk_add_f32 v[28:29], v[28:29], 1.0 op_sel_hi:[1,0]
	v_pk_add_f32 v[30:31], v[30:31], 1.0 op_sel_hi:[1,0]
	v_pk_add_f32 v[20:21], v[20:21], 1.0 op_sel_hi:[1,0]
	v_pk_add_f32 v[22:23], v[22:23], 1.0 op_sel_hi:[1,0]
	v_rcp_f32_e32 v28, v28
	v_rcp_f32_e32 v29, v29
	v_rcp_f32_e32 v30, v30
	v_rcp_f32_e32 v31, v31
	v_rcp_f32_e32 v20, v20
	v_rcp_f32_e32 v21, v21
	v_rcp_f32_e32 v22, v22
	v_rcp_f32_e32 v23, v23
	v_pk_mul_f32 v[24:25], v[24:25], v[28:29]
	v_pk_mul_f32 v[26:27], v[26:27], v[30:31]
	v_pk_mul_f32 v[16:17], v[16:17], v[20:21]
	v_pk_mul_f32 v[18:19], v[18:19], v[22:23]
	v_cvt_pk_bf16_f32 v28, v24, v25
	v_cvt_pk_bf16_f32 v29, v26, v27
	v_cvt_pk_bf16_f32 v30, v16, v17
	v_cvt_pk_bf16_f32 v31, v18, v19
	s_mov_b32 s26, 0xdc000
	s_mov_b32 s27, 0
	v_lshl_add_u64 v[38:39], v[150:151], 0, s[26:27]
	global_store_dwordx4 v[38:39], v[28:31], off
	v_pk_mul_f32 v[8:9], v[12:13], v[8:9]
	v_pk_mul_f32 v[10:11], v[14:15], v[10:11]
	v_pk_mul_f32 v[0:1], v[4:5], v[0:1]
	v_pk_mul_f32 v[2:3], v[6:7], v[2:3]
	v_pk_mul_f32 v[12:13], v[12:13], vcc op_sel_hi:[1,0]
	v_pk_mul_f32 v[14:15], v[14:15], vcc op_sel_hi:[1,0]
	v_pk_mul_f32 v[4:5], v[4:5], vcc op_sel_hi:[1,0]
	v_pk_mul_f32 v[6:7], v[6:7], vcc op_sel_hi:[1,0]
	v_exp_f32_e32 v12, v12
	v_exp_f32_e32 v13, v13
	v_exp_f32_e32 v14, v14
	v_exp_f32_e32 v15, v15
	v_exp_f32_e32 v4, v4
	v_exp_f32_e32 v5, v5
	v_exp_f32_e32 v6, v6
	v_exp_f32_e32 v7, v7
	v_pk_add_f32 v[12:13], v[12:13], 1.0 op_sel_hi:[1,0]
	v_pk_add_f32 v[14:15], v[14:15], 1.0 op_sel_hi:[1,0]
	v_pk_add_f32 v[4:5], v[4:5], 1.0 op_sel_hi:[1,0]
	v_pk_add_f32 v[6:7], v[6:7], 1.0 op_sel_hi:[1,0]
	v_rcp_f32_e32 v12, v12
	v_rcp_f32_e32 v13, v13
	v_rcp_f32_e32 v14, v14
	v_rcp_f32_e32 v15, v15
	v_rcp_f32_e32 v4, v4
	v_rcp_f32_e32 v5, v5
	v_rcp_f32_e32 v6, v6
	v_rcp_f32_e32 v7, v7
	v_pk_mul_f32 v[8:9], v[8:9], v[12:13]
	v_pk_mul_f32 v[10:11], v[10:11], v[14:15]
	v_pk_mul_f32 v[0:1], v[0:1], v[4:5]
	v_pk_mul_f32 v[2:3], v[2:3], v[6:7]
	v_cvt_pk_bf16_f32 v12, v8, v9
	v_cvt_pk_bf16_f32 v13, v10, v11
	v_cvt_pk_bf16_f32 v14, v0, v1
	v_cvt_pk_bf16_f32 v15, v2, v3
	s_mov_b32 s26, 0xf2000
	s_mov_b32 s27, 0
	v_lshl_add_u64 v[16:17], v[150:151], 0, s[26:27]
	global_store_dwordx4 v[16:17], v[12:15], off
	s_branch .LBB0_90
